# K-loop static priority: the lower-numbered of the two co-resident workgroups runs its GEMM K-loops at s_setprio 1 (on top of the early-DMA schedule)
# speedup vs baseline: 1.0142x; 1.0075x over previous
; template <int EPI, int MI>
; DI void gemm_tile(const GemmDesc& g, int tm, int tn, char* smem) {
;     ...
;   const int rowA = wm * (32 * MI) + r, rowB = wn * 64 + r;
;   const int hk = hh ^ ((r & 7) ^ ((r >> 3) & 3));
;     ...
;   G_GLDS(0, 0);
;   asm volatile("s_waitcnt vmcnt(0)" ::: "memory");
;   __syncthreads();
;   for (int kt = 0; kt < nk; kt += 2) {
;     if (kt + 1 < nk) G_GLDS(kt + 1, 1);
;     G_COMPUTE(0);
.Lga_noprio:
	v_add_u32_e32 v162, v155, v157
	v_add_u32_e32 v163, v155, v159
	v_add_u32_e32 v164, v155, v160
	v_add_u32_e32 v165, v155, v161
	v_add_u32_e32 v166, v156, v157
	v_add_u32_e32 v167, v156, v159
	v_add_u32_e32 v168, v156, v160
	v_add_u32_e32 v169, v156, v161
	v_add_u32_e32 v170, v158, v157
	v_add_u32_e32 v171, v158, v159
	v_add_u32_e32 v172, v158, v160
	v_add_u32_e32 v173, v158, v161
	v_lshl_add_u64 v[174:175], v[104:105], 0, v[100:101]
	v_lshl_add_u64 v[176:177], v[102:103], 0, v[100:101]
	v_readfirstlane_b32 s100, v124
	s_waitcnt vmcnt(0) lgkmcnt(0)
	s_barrier
	s_add_u32 m0, s100, 0x6000
	v_lshl_add_u64 v[106:107], v[174:175], 0, s[96:97]
	global_load_lds_dwordx4 v[106:107], off
	s_add_u32 m0, s100, 0x7000
	v_lshl_add_u64 v[106:107], v[174:175], 0, s[50:51]
	global_load_lds_dwordx4 v[106:107], off
	s_add_u32 m0, s100, 0x8000
	v_lshl_add_u64 v[106:107], v[174:175], 0, s[24:25]
	global_load_lds_dwordx4 v[106:107], off
	s_add_u32 m0, s100, 0x9000
	v_lshl_add_u64 v[106:107], v[174:175], 0, s[26:27]
	global_load_lds_dwordx4 v[106:107], off
	ds_read_b128 v[236:239], v166 offset:49152
	ds_read_b128 v[240:243], v166 offset:53248
	ds_read_b128 v[224:227], v162
	ds_read_b128 v[228:231], v162 offset:4096
	s_mov_b32 s15, 0

; template <int EPI, int MI>
; DI void gemm_tile(const GemmDesc& g, int tm, int tn, char* smem) {
;     ...
;   const int rowA = wm * (32 * MI) + r, rowB = wn * 64 + r;
;   const int hk = hh ^ ((r & 7) ^ ((r >> 3) & 3));
;     ...
;   G_GLDS(0, 0);
;   asm volatile("s_waitcnt vmcnt(0)" ::: "memory");
;   __syncthreads();
;   for (int kt = 0; kt < nk; kt += 2) {
;     if (kt + 1 < nk) G_GLDS(kt + 1, 1);
;     G_COMPUTE(0);
.Lgd_noprio:
	v_add_u32_e32 v162, v131, v154
	v_add_u32_e32 v163, v131, v156
	v_add_u32_e32 v164, v131, v157
	v_add_u32_e32 v165, v131, v158
	v_add_u32_e32 v166, v153, v154
	v_add_u32_e32 v167, v153, v156
	v_add_u32_e32 v168, v153, v157
	v_add_u32_e32 v169, v153, v158
	v_add_u32_e32 v170, v155, v154
	v_add_u32_e32 v171, v155, v156
	v_add_u32_e32 v172, v155, v157
	v_add_u32_e32 v173, v155, v158
	v_lshl_add_u64 v[252:253], v[100:101], 0, v[98:99]
	v_lshl_add_u64 v[254:255], v[102:103], 0, v[98:99]
	v_readfirstlane_b32 s100, v121
	s_mov_b64 s[4:5], 0x80
	s_waitcnt vmcnt(0) lgkmcnt(0)
	s_barrier
	s_mov_b64 s[16:17], 0x5872080
	s_add_u32 m0, s100, 0x6000
	v_lshl_add_u64 v[106:107], v[252:253], 0, s[16:17]
	global_load_lds_dwordx4 v[106:107], off
	s_mov_b64 s[16:17], 0x589e080
	s_add_u32 m0, s100, 0x7000
	v_lshl_add_u64 v[106:107], v[252:253], 0, s[16:17]
	global_load_lds_dwordx4 v[106:107], off
	s_mov_b64 s[16:17], 0x58ca080
	s_add_u32 m0, s100, 0x8000
	v_lshl_add_u64 v[106:107], v[252:253], 0, s[16:17]
	global_load_lds_dwordx4 v[106:107], off
	s_mov_b64 s[16:17], 0x58f6080
	s_add_u32 m0, s100, 0x9000
	v_lshl_add_u64 v[106:107], v[252:253], 0, s[16:17]
	global_load_lds_dwordx4 v[106:107], off
	s_mov_b64 s[16:17], 0x5922080
	s_add_u32 m0, s100, 0xa000
	v_lshl_add_u64 v[106:107], v[252:253], 0, s[16:17]
	global_load_lds_dwordx4 v[106:107], off
	s_mov_b64 s[16:17], 0x594e080
	s_add_u32 m0, s100, 0xb000
	v_lshl_add_u64 v[106:107], v[252:253], 0, s[16:17]
	global_load_lds_dwordx4 v[106:107], off
	v_lshl_add_u64 v[252:253], v[252:253], 0, s[4:5]
	s_mov_b64 s[16:17], 0x1600080
	s_add_u32 m0, s100, 0x10000
	v_lshl_add_u64 v[106:107], v[254:255], 0, s[16:17]
	global_load_lds_dwordx4 v[106:107], off
	s_mov_b64 s[16:17], 0x162c080
	s_add_u32 m0, s100, 0x11000
	v_lshl_add_u64 v[106:107], v[254:255], 0, s[16:17]
	global_load_lds_dwordx4 v[106:107], off
	s_mov_b64 s[16:17], 0x1658080
	s_add_u32 m0, s100, 0x12000
	v_lshl_add_u64 v[106:107], v[254:255], 0, s[16:17]
	global_load_lds_dwordx4 v[106:107], off
	s_mov_b64 s[16:17], 0x1684080
	s_add_u32 m0, s100, 0x13000
	v_lshl_add_u64 v[106:107], v[254:255], 0, s[16:17]
	global_load_lds_dwordx4 v[106:107], off
	v_lshl_add_u64 v[254:255], v[254:255], 0, s[4:5]
	ds_read_b128 v[236:239], v166 offset:49152
	ds_read_b128 v[240:243], v166 offset:53248
	ds_read_b128 v[224:227], v162
	ds_read_b128 v[228:231], v162 offset:4096
	s_mov_b32 s15, 0

; template <int EPI, int MI>
; DI void gemm_tile(const GemmDesc& g, int tm, int tn, char* smem) {
;     ...
;   const int rowA = wm * (32 * MI) + r, rowB = wn * 64 + r;
;   const int hk = hh ^ ((r & 7) ^ ((r >> 3) & 3));
;     ...
;   G_GLDS(0, 0);
;   asm volatile("s_waitcnt vmcnt(0)" ::: "memory");
;   __syncthreads();
;   for (int kt = 0; kt < nk; kt += 2) {
;     if (kt + 1 < nk) G_GLDS(kt + 1, 1);
;     G_COMPUTE(0);
.Lgw_noprio:
	v_add_u32_e32 v162, v131, v154
	v_add_u32_e32 v163, v131, v156
	v_add_u32_e32 v164, v131, v157
	v_add_u32_e32 v165, v131, v158
	v_add_u32_e32 v166, v153, v154
	v_add_u32_e32 v167, v153, v156
	v_add_u32_e32 v168, v153, v157
	v_add_u32_e32 v169, v153, v158
	v_add_u32_e32 v170, v155, v154
	v_add_u32_e32 v171, v155, v156
	v_add_u32_e32 v172, v155, v157
	v_add_u32_e32 v173, v155, v158
	v_lshl_add_u64 v[252:253], v[102:103], 0, v[98:99]
	v_lshl_add_u64 v[254:255], v[100:101], 0, v[98:99]
	v_readfirstlane_b32 s100, v121
	s_mov_b64 s[0:1], 0x80
	s_waitcnt vmcnt(0) lgkmcnt(0)
	s_barrier
	s_add_u32 m0, s100, 0x6000
	v_lshl_add_u64 v[106:107], v[252:253], 0, s[96:97]
	global_load_lds_dwordx4 v[106:107], off
	s_add_u32 m0, s100, 0x7000
	v_lshl_add_u64 v[106:107], v[252:253], 0, s[50:51]
	global_load_lds_dwordx4 v[106:107], off
	s_add_u32 m0, s100, 0x8000
	v_lshl_add_u64 v[106:107], v[252:253], 0, s[24:25]
	global_load_lds_dwordx4 v[106:107], off
	s_add_u32 m0, s100, 0x9000
	v_lshl_add_u64 v[106:107], v[252:253], 0, s[26:27]
	global_load_lds_dwordx4 v[106:107], off
	ds_read_b128 v[236:239], v166 offset:49152
	ds_read_b128 v[240:243], v166 offset:53248
	ds_read_b128 v[224:227], v162
	ds_read_b128 v[228:231], v162 offset:4096
	s_mov_b32 s101, 0

; template <int EPI, int MI>
; DI void gemm_tile(const GemmDesc& g, int tm, int tn, char* smem) {
;     ...
;   const int rowA = wm * (32 * MI) + r, rowB = wn * 64 + r;
;   const int hk = hh ^ ((r & 7) ^ ((r >> 3) & 3));
;     ...
;   G_GLDS(0, 0);
;   asm volatile("s_waitcnt vmcnt(0)" ::: "memory");
;   __syncthreads();
;   for (int kt = 0; kt < nk; kt += 2) {
;     if (kt + 1 < nk) G_GLDS(kt + 1, 1);
;     G_COMPUTE(0);
.Lgc_noprio:
	v_add_u32_e32 v98, v89, v91
	v_add_u32_e32 v99, v89, v92
	v_add_u32_e32 v100, v89, v93
	v_add_u32_e32 v101, v89, v94
	v_add_u32_e32 v102, v90, v91
	v_add_u32_e32 v103, v90, v92
	v_add_u32_e32 v104, v90, v93
	v_add_u32_e32 v105, v90, v94
	v_lshl_add_u64 v[72:73], v[68:69], 0, v[66:67]
	v_lshl_add_u64 v[74:75], v[70:71], 0, v[66:67]
	v_readfirstlane_b32 s100, v65
	s_mov_b64 s[44:45], 0x80
	s_waitcnt vmcnt(0) lgkmcnt(0)
	s_barrier
	s_add_u32 m0, s100, 0x4000
	v_lshl_add_u64 v[106:107], v[72:73], 0, s[96:97]
	global_load_lds_dwordx4 v[106:107], off
	s_add_u32 m0, s100, 0x5000
	v_lshl_add_u64 v[106:107], v[72:73], 0, s[50:51]
	global_load_lds_dwordx4 v[106:107], off
	s_add_u32 m0, s100, 0x6000
	v_lshl_add_u64 v[106:107], v[72:73], 0, s[24:25]
	global_load_lds_dwordx4 v[106:107], off
	s_add_u32 m0, s100, 0x7000
	v_lshl_add_u64 v[106:107], v[72:73], 0, s[26:27]
	global_load_lds_dwordx4 v[106:107], off
	v_lshl_add_u64 v[72:73], v[72:73], 0, s[44:45]
	ds_read_b128 v[240:243], v102 offset:32768
	ds_read_b128 v[244:247], v102 offset:36864
	ds_read_b128 v[224:227], v98
	ds_read_b128 v[228:231], v98 offset:4096
	s_mov_b32 s101, 0

; template <int EPI, int MI>
; DI void gemm_tile(const GemmDesc& g, int tm, int tn, char* smem) {
;     ...
;   const int rowA = wm * (32 * MI) + r, rowB = wn * 64 + r;
;   const int hk = hh ^ ((r & 7) ^ ((r >> 3) & 3));
;     ...
;   G_GLDS(0, 0);
;   asm volatile("s_waitcnt vmcnt(0)" ::: "memory");
;   __syncthreads();
;   for (int kt = 0; kt < nk; kt += 2) {
;     if (kt + 1 < nk) G_GLDS(kt + 1, 1);
;     G_COMPUTE(0);
.Lgb_noprio:
	v_add_u32_e32 v162, v155, v157
	v_add_u32_e32 v163, v155, v159
	v_add_u32_e32 v164, v155, v160
	v_add_u32_e32 v165, v155, v161
	v_add_u32_e32 v166, v156, v157
	v_add_u32_e32 v167, v156, v159
	v_add_u32_e32 v168, v156, v160
	v_add_u32_e32 v169, v156, v161
	v_add_u32_e32 v170, v158, v157
	v_add_u32_e32 v171, v158, v159
	v_add_u32_e32 v172, v158, v160
	v_add_u32_e32 v173, v158, v161
	v_lshl_add_u64 v[252:253], v[102:103], 0, v[100:101]
	v_lshl_add_u64 v[254:255], v[104:105], 0, v[100:101]
	v_readfirstlane_b32 s100, v124
	s_mov_b64 s[0:1], 0x80
	s_waitcnt vmcnt(0) lgkmcnt(0)
	s_barrier
	s_add_u32 m0, s100, 0x6000
	v_lshl_add_u64 v[106:107], v[252:253], 0, s[96:97]
	global_load_lds_dwordx4 v[106:107], off
	s_add_u32 m0, s100, 0x7000
	v_lshl_add_u64 v[106:107], v[252:253], 0, s[50:51]
	global_load_lds_dwordx4 v[106:107], off
	s_add_u32 m0, s100, 0x8000
	v_lshl_add_u64 v[106:107], v[252:253], 0, s[24:25]
	global_load_lds_dwordx4 v[106:107], off
	s_add_u32 m0, s100, 0x9000
	v_lshl_add_u64 v[106:107], v[252:253], 0, s[26:27]
	global_load_lds_dwordx4 v[106:107], off
	s_add_u32 m0, s100, 0xa000
	v_lshl_add_u64 v[106:107], v[252:253], 0, s[28:29]
	global_load_lds_dwordx4 v[106:107], off
	s_add_u32 m0, s100, 0xb000
	v_lshl_add_u64 v[106:107], v[252:253], 0, s[30:31]
	global_load_lds_dwordx4 v[106:107], off
	v_lshl_add_u64 v[252:253], v[252:253], 0, s[0:1]
	s_mov_b64 s[16:17], 0xb00080
	s_add_u32 m0, s100, 0x10000
	v_lshl_add_u64 v[106:107], v[254:255], 0, s[16:17]
	global_load_lds_dwordx4 v[106:107], off
	s_mov_b64 s[16:17], 0xb10080
	s_add_u32 m0, s100, 0x11000
	v_lshl_add_u64 v[106:107], v[254:255], 0, s[16:17]
	global_load_lds_dwordx4 v[106:107], off
	s_mov_b64 s[16:17], 0xb20080
	s_add_u32 m0, s100, 0x12000
	v_lshl_add_u64 v[106:107], v[254:255], 0, s[16:17]
	global_load_lds_dwordx4 v[106:107], off
	s_mov_b64 s[16:17], 0xb30080
	s_add_u32 m0, s100, 0x13000
	v_lshl_add_u64 v[106:107], v[254:255], 0, s[16:17]
	global_load_lds_dwordx4 v[106:107], off
	v_lshl_add_u64 v[254:255], v[254:255], 0, s[0:1]
	ds_read_b128 v[236:239], v166 offset:49152
	ds_read_b128 v[240:243], v166 offset:53248
	ds_read_b128 v[224:227], v162
	ds_read_b128 v[228:231], v162 offset:4096
	s_mov_b32 s101, 0

; template <int EPI, int MI>
; DI void gemm_tile(const GemmDesc& g, int tm, int tn, char* smem) {
;     ...
;   const int rowA = wm * (32 * MI) + r, rowB = wn * 64 + r;
;   const int hk = hh ^ ((r & 7) ^ ((r >> 3) & 3));
;     ...
;   G_GLDS(0, 0);
;   asm volatile("s_waitcnt vmcnt(0)" ::: "memory");
;   __syncthreads();
;   for (int kt = 0; kt < nk; kt += 2) {
;     if (kt + 1 < nk) G_GLDS(kt + 1, 1);
;     G_COMPUTE(0);
.Lgf_noprio:
	v_add_u32_e32 v92, v86, v88
	v_add_u32_e32 v93, v86, v89
	v_add_u32_e32 v94, v86, v90
	v_add_u32_e32 v95, v86, v91
	v_add_u32_e32 v97, v87, v88
	v_add_u32_e32 v98, v87, v89
	v_add_u32_e32 v99, v87, v90
	v_add_u32_e32 v100, v87, v91
	v_lshl_add_u64 v[104:105], v[66:67], 0, v[64:65]
	v_lshl_add_u64 v[106:107], v[68:69], 0, v[64:65]
	v_readfirstlane_b32 s100, v78
	s_mov_b64 s[46:47], 0x80
	s_waitcnt vmcnt(0) lgkmcnt(0)
	s_barrier
	s_mov_b64 s[4:5], 0x5872080
	s_add_u32 m0, s100, 0x4000
	v_lshl_add_u64 v[102:103], v[104:105], 0, s[4:5]
	global_load_lds_dwordx4 v[102:103], off
	s_mov_b64 s[4:5], 0x589e080
	s_add_u32 m0, s100, 0x5000
	v_lshl_add_u64 v[102:103], v[104:105], 0, s[4:5]
	global_load_lds_dwordx4 v[102:103], off
	s_mov_b64 s[4:5], 0x58ca080
	s_add_u32 m0, s100, 0x6000
	v_lshl_add_u64 v[102:103], v[104:105], 0, s[4:5]
	global_load_lds_dwordx4 v[102:103], off
	s_mov_b64 s[4:5], 0x58f6080
	s_add_u32 m0, s100, 0x7000
	v_lshl_add_u64 v[102:103], v[104:105], 0, s[4:5]
	global_load_lds_dwordx4 v[102:103], off
	v_lshl_add_u64 v[104:105], v[104:105], 0, s[46:47]
	ds_read_b128 v[240:243], v97 offset:32768
	ds_read_b128 v[244:247], v97 offset:36864
	ds_read_b128 v[224:227], v92
	ds_read_b128 v[228:231], v92 offset:4096
	s_mov_b32 s101, 0

; template <int EPI, int MI>
; DI void gemm_tile(const GemmDesc& g, int tm, int tn, char* smem) {
;     ...
;   const int rowA = wm * (32 * MI) + r, rowB = wn * 64 + r;
;   const int hk = hh ^ ((r & 7) ^ ((r >> 3) & 3));
;     ...
;   G_GLDS(0, 0);
;   asm volatile("s_waitcnt vmcnt(0)" ::: "memory");
;   __syncthreads();
;   for (int kt = 0; kt < nk; kt += 2) {
;     if (kt + 1 < nk) G_GLDS(kt + 1, 1);
;     G_COMPUTE(0);
.Lge_noprio:
	v_add_u32_e32 v162, v131, v154
	v_add_u32_e32 v163, v131, v156
	v_add_u32_e32 v164, v131, v157
	v_add_u32_e32 v165, v131, v158
	v_add_u32_e32 v166, v153, v154
	v_add_u32_e32 v167, v153, v156
	v_add_u32_e32 v168, v153, v157
	v_add_u32_e32 v169, v153, v158
	v_add_u32_e32 v170, v155, v154
	v_add_u32_e32 v171, v155, v156
	v_add_u32_e32 v172, v155, v157
	v_add_u32_e32 v173, v155, v158
	v_lshl_add_u64 v[252:253], v[100:101], 0, v[98:99]
	v_lshl_add_u64 v[254:255], v[102:103], 0, v[98:99]
	v_readfirstlane_b32 s100, v121
	s_mov_b64 s[4:5], 0x80
	s_waitcnt vmcnt(0) lgkmcnt(0)
	s_barrier
	s_mov_b64 s[16:17], 0x5872080
	s_add_u32 m0, s100, 0x6000
	v_lshl_add_u64 v[106:107], v[252:253], 0, s[16:17]
	global_load_lds_dwordx4 v[106:107], off
	s_mov_b64 s[16:17], 0x589e080
	s_add_u32 m0, s100, 0x7000
	v_lshl_add_u64 v[106:107], v[252:253], 0, s[16:17]
	global_load_lds_dwordx4 v[106:107], off
	s_mov_b64 s[16:17], 0x58ca080
	s_add_u32 m0, s100, 0x8000
	v_lshl_add_u64 v[106:107], v[252:253], 0, s[16:17]
	global_load_lds_dwordx4 v[106:107], off
	s_mov_b64 s[16:17], 0x58f6080
	s_add_u32 m0, s100, 0x9000
	v_lshl_add_u64 v[106:107], v[252:253], 0, s[16:17]
	global_load_lds_dwordx4 v[106:107], off
	s_mov_b64 s[16:17], 0x5922080
	s_add_u32 m0, s100, 0xa000
	v_lshl_add_u64 v[106:107], v[252:253], 0, s[16:17]
	global_load_lds_dwordx4 v[106:107], off
	s_mov_b64 s[16:17], 0x594e080
	s_add_u32 m0, s100, 0xb000
	v_lshl_add_u64 v[106:107], v[252:253], 0, s[16:17]
	global_load_lds_dwordx4 v[106:107], off
	v_lshl_add_u64 v[252:253], v[252:253], 0, s[4:5]
	s_mov_b64 s[16:17], 0x1b80080
	s_add_u32 m0, s100, 0x10000
	v_lshl_add_u64 v[106:107], v[254:255], 0, s[16:17]
	global_load_lds_dwordx4 v[106:107], off
	s_mov_b64 s[16:17], 0x1bac080
	s_add_u32 m0, s100, 0x11000
	v_lshl_add_u64 v[106:107], v[254:255], 0, s[16:17]
	global_load_lds_dwordx4 v[106:107], off
	s_mov_b64 s[16:17], 0x1bd8080
	s_add_u32 m0, s100, 0x12000
	v_lshl_add_u64 v[106:107], v[254:255], 0, s[16:17]
	global_load_lds_dwordx4 v[106:107], off
	s_mov_b64 s[16:17], 0x1c04080
	s_add_u32 m0, s100, 0x13000
	v_lshl_add_u64 v[106:107], v[254:255], 0, s[16:17]
	global_load_lds_dwordx4 v[106:107], off
	v_lshl_add_u64 v[254:255], v[254:255], 0, s[4:5]
	ds_read_b128 v[236:239], v166 offset:49152
	ds_read_b128 v[240:243], v166 offset:53248
	ds_read_b128 v[224:227], v162
	ds_read_b128 v[228:231], v162 offset:4096
	s_mov_b32 s15, 0
